# attention rel-bias: blocks whose key offsets all clamp to -256 take one broadcast table read instead of 96 index ops and 32 gathers (wave-uniform dynamic test)
# baseline (speedup 1.0000x reference)
; #define MFMA32(a, b, c) __builtin_amdgcn_mfma_f32_32x32x16_f16((a), (b), (c), 0, 0, 0)
; DI int crow(int i, int h) { return (i & 3) + 8 * (i >> 2) + 4 * h; }
; template <int HD, int BIAS, bool FULL>
; DI void attn_block(const bf16_t* Kb, int ktb, const bf16_t* Vb, int vtb, int koff, int kpos0, int qp, float slope, const float* rel,
;                    const bf16x8 (&qf)[HD / 16], f32x16 (&o)[HD / 32], float& m, float& l) {
;     ...
;     bf16x8 kreg[NKT][KSQ];
; #pragma unroll
;     for (int kt = 0; kt < NKT; ++kt)
; #pragma unroll
;         for (int ks = 0; ks < KSQ; ++ks) kreg[kt][ks] = *(const bf16x8*)(Kb + (size_t)kt * ktb + ks * 512 + lane * 8);
;     constexpr int NS = FULL ? 4 : 1;
;     bf16x8 vreg[DT][NS];
;     auto loadV = [&]() {
; #pragma unroll
;         for (int si = 0; si < NS; ++si)
; #pragma unroll
;             for (int dt = 0; dt < DT; ++dt) { const int s = FULL ? si : s0; vreg[dt][si] = *(const bf16x8*)(Vb + (size_t)(s >> 1) * vtb + dt * 1024 + (s & 1) * 512 + lane * 8); }
;     };
;     if (VTOP) loadV();
;     __builtin_amdgcn_sched_barrier(0);
;     f32x16 st[NKT];
; #pragma unroll
;     for (int kt = 0; kt < NKT; ++kt) {
; #pragma unroll
;         for (int i = 0; i < 16; ++i) st[kt][i] = 0.f;
; #pragma unroll
;         for (int ks = 0; ks < KSQ; ++ks) st[kt] = MFMA32(kreg[kt][ks], qf[ks], st[kt]);
;     }
;     __builtin_amdgcn_sched_barrier(0);
;     if (!VTOP) loadV();
;     float mx = -1e30f;
; #pragma unroll
;     for (int kt = 0; kt < NKT; ++kt)
; #pragma unroll
;         for (int i = 0; i < 16; ++i) {
;             const int key = kt * 32 + crow(i, h);
;             float s = st[kt][i];
;             const int dk = dq + (kt * 32 + (i & 3) + 8 * (i >> 2));
;             if (BIAS == 1) s -= slope * (float)(dk < 0 ? -dk : dk);
;             if (BIAS == 2) { int d = dk < -256 ? -256 : (dk > 256 ? 256 : dk); s += rel[d + 256]; }
.LBB0_329:
	v_mov_b32_e32 v0, v176
	s_add_u32 s28, s2, s0
	v_lshrrev_b32_e32 v34, 3, v0
	v_and_b32_e32 v0, 63, v0
	v_lshlrev_b32_e32 v0, 4, v0
	s_addc_u32 s29, s3, s1
	v_lshl_add_u64 v[50:51], s[28:29], 0, v[0:1]
	s_mov_b32 s28, 0x18406000
	v_add_co_u32_e32 v46, vcc, s28, v50
	s_mov_b32 s28, 0x1840e000
	s_nop 0
	v_addc_co_u32_e32 v47, vcc, 0, v51, vcc
	v_and_b32_e32 v34, 4, v34
	v_add_co_u32_e32 v52, vcc, s28, v50
	s_waitcnt vmcnt(4)
	v_add_u32_e32 v120, v118, v34
	v_addc_co_u32_e32 v53, vcc, 0, v51, vcc
	s_mov_b32 s28, 0x18806000
	global_load_dwordx4 v[34:37], v[46:47], off
	global_load_dwordx4 v[38:41], v[46:47], off offset:1024
	global_load_dwordx4 v[42:45], v[46:47], off offset:2048
	s_nop 0
	global_load_dwordx4 v[46:49], v[46:47], off offset:3072
	s_nop 0
	global_load_dwordx4 v[122:125], v[52:53], off
	global_load_dwordx4 v[126:129], v[52:53], off offset:1024
	global_load_dwordx4 v[130:133], v[52:53], off offset:2048
	global_load_dwordx4 v[134:137], v[52:53], off offset:3072
	v_add_co_u32_e32 v52, vcc, s28, v50
	s_mov_b32 s28, 0x1880e000
	s_nop 0
	v_addc_co_u32_e32 v53, vcc, 0, v51, vcc
	v_add_co_u32_e32 v50, vcc, s28, v50
	global_load_dwordx4 v[110:113], v[52:53], off
	global_load_dwordx4 v[102:105], v[52:53], off offset:1024
	global_load_dwordx4 v[106:109], v[52:53], off offset:2048
	global_load_dwordx4 v[98:101], v[52:53], off offset:3072
	v_addc_co_u32_e32 v51, vcc, 0, v51, vcc
	global_load_dwordx4 v[94:97], v[50:51], off
	global_load_dwordx4 v[86:89], v[50:51], off offset:1024
	global_load_dwordx4 v[90:93], v[50:51], off offset:2048
	global_load_dwordx4 v[82:85], v[50:51], off offset:3072
	v_mov_b32_e32 v121, v58
	v_mov_b32_e32 v119, v59
	s_waitcnt vmcnt(15)
	v_mfma_f32_32x32x16_f16 v[50:65], v[34:37], v[78:81], 0
	s_waitcnt vmcnt(14)
	v_mfma_f32_32x32x16_f16 v[50:65], v[38:41], v[74:77], v[50:65]
	s_waitcnt vmcnt(13)
	v_mfma_f32_32x32x16_f16 v[50:65], v[42:45], v[66:69], v[50:65]
	s_waitcnt vmcnt(12)
	v_mfma_f32_32x32x16_f16 v[50:65], v[46:49], v[70:73], v[50:65]
	s_waitcnt vmcnt(11)
	v_mfma_f32_32x32x16_f16 v[34:49], v[122:125], v[78:81], 0
	s_waitcnt vmcnt(10)
	v_mfma_f32_32x32x16_f16 v[34:49], v[126:129], v[74:77], v[34:49]
	s_waitcnt vmcnt(9)
	v_mfma_f32_32x32x16_f16 v[34:49], v[130:133], v[66:69], v[34:49]
	s_waitcnt vmcnt(8)
	v_mfma_f32_32x32x16_f16 v[34:49], v[134:137], v[70:73], v[34:49]
	v_cmp_lt_i32_e32 vcc, 0xfffffec5, v120
	s_cbranch_vccnz .Lbf_s3_slow
	v_mov_b32_e32 v142, s61
	ds_read_b32 v143, v142
	ds_read_b32 v144, v142
	ds_read_b32 v145, v142
	ds_read_b32 v146, v142
	ds_read_b32 v147, v142
	ds_read_b32 v148, v142
	ds_read_b32 v149, v142
	ds_read_b32 v150, v142
	ds_read_b32 v151, v142
	ds_read_b32 v152, v142
	ds_read_b32 v153, v142
	ds_read_b32 v154, v142
	ds_read_b32 v155, v142
	ds_read_b32 v156, v142
	ds_read_b32 v157, v142
	ds_read_b32 v158, v142
	ds_read_b32 v159, v142
	ds_read_b32 v160, v142
	ds_read_b32 v161, v142
	ds_read_b32 v162, v142
	ds_read_b32 v163, v142
	ds_read_b32 v164, v142
	ds_read_b32 v165, v142
	ds_read_b32 v166, v142
	ds_read_b32 v167, v142
	ds_read_b32 v168, v142
	ds_read_b32 v169, v142
	ds_read_b32 v170, v142
	ds_read_b32 v171, v142
	ds_read_b32 v172, v142
	ds_read_b32 v173, v142
	ds_read_b32 v142, v142
	s_branch .Lbf_s3_join
.Lbf_s3_slow:
	v_add_u32_e32 v142, 2, v120
	v_med3_i32 v142, v142, s45, v186
	v_lshl_add_u32 v142, v142, 2, s61
	ds_read_b32 v142, v142 offset:1024
	v_med3_i32 v143, v120, s45, v186
	v_lshl_add_u32 v143, v143, 2, s61
	ds_read_b32 v143, v143 offset:1024
	v_add_u32_e32 v144, 3, v120
	v_med3_i32 v144, v144, s45, v186
	v_lshl_add_u32 v144, v144, 2, s61
	ds_read_b32 v144, v144 offset:1024
	v_add_u32_e32 v145, 8, v120
	v_med3_i32 v145, v145, s45, v186
	v_lshl_add_u32 v145, v145, 2, s61
	ds_read_b32 v145, v145 offset:1024
	v_add_u32_e32 v146, 9, v120
	v_med3_i32 v146, v146, s45, v186
	v_lshl_add_u32 v146, v146, 2, s61
	ds_read_b32 v146, v146 offset:1024
	v_add_u32_e32 v147, 10, v120
	v_med3_i32 v147, v147, s45, v186
	v_lshl_add_u32 v147, v147, 2, s61
	ds_read_b32 v147, v147 offset:1024
	v_add_u32_e32 v148, 11, v120
	v_med3_i32 v148, v148, s45, v186
	v_lshl_add_u32 v148, v148, 2, s61
	ds_read_b32 v148, v148 offset:1024
	v_add_u32_e32 v149, 16, v120
	v_med3_i32 v149, v149, s45, v186
	v_lshl_add_u32 v149, v149, 2, s61
	ds_read_b32 v149, v149 offset:1024
	v_add_u32_e32 v150, 17, v120
	v_med3_i32 v150, v150, s45, v186
	v_lshl_add_u32 v150, v150, 2, s61
	ds_read_b32 v150, v150 offset:1024
	v_add_u32_e32 v151, 1, v120
	v_med3_i32 v151, v151, s45, v186
	v_lshl_add_u32 v151, v151, 2, s61
	v_add_u32_e32 v152, 18, v120
	v_med3_i32 v152, v152, s45, v186
	v_lshl_add_u32 v152, v152, 2, s61
	ds_read_b32 v151, v151 offset:1024
	ds_read_b32 v152, v152 offset:1024
	v_add_u32_e32 v153, 19, v120
	v_med3_i32 v153, v153, s45, v186
	v_lshl_add_u32 v153, v153, 2, s61
	ds_read_b32 v153, v153 offset:1024
	v_add_u32_e32 v154, 24, v120
	v_med3_i32 v154, v154, s45, v186
	v_lshl_add_u32 v154, v154, 2, s61
	ds_read_b32 v154, v154 offset:1024
	v_add_u32_e32 v155, 25, v120
	v_med3_i32 v155, v155, s45, v186
	v_lshl_add_u32 v155, v155, 2, s61
	ds_read_b32 v155, v155 offset:1024
	v_add_u32_e32 v156, 26, v120
	v_med3_i32 v156, v156, s45, v186
	v_lshl_add_u32 v156, v156, 2, s61
	ds_read_b32 v156, v156 offset:1024
	v_add_u32_e32 v157, 27, v120
	v_med3_i32 v157, v157, s45, v186
	v_lshl_add_u32 v157, v157, 2, s61
	ds_read_b32 v157, v157 offset:1024
	v_add_u32_e32 v158, 32, v120
	v_med3_i32 v158, v158, s45, v186
	v_lshl_add_u32 v158, v158, 2, s61
	ds_read_b32 v158, v158 offset:1024
	v_add_u32_e32 v159, 33, v120
	v_med3_i32 v159, v159, s45, v186
	v_lshl_add_u32 v159, v159, 2, s61
	ds_read_b32 v159, v159 offset:1024
; DI int crow(int i, int h) { return (i & 3) + 8 * (i >> 2) + 4 * h; }
; template <int HD, int BIAS, bool FULL>
; DI void attn_block(const bf16_t* Kb, int ktb, const bf16_t* Vb, int vtb, int koff, int kpos0, int qp, float slope, const float* rel,
;                    const bf16x8 (&qf)[HD / 16], f32x16 (&o)[HD / 32], float& m, float& l) {
;     ...
;     for (int kt = 0; kt < NKT; ++kt)
; #pragma unroll
;         for (int i = 0; i < 16; ++i) {
;             const int key = kt * 32 + crow(i, h);
;             float s = st[kt][i];
;             const int dk = dq + (kt * 32 + (i & 3) + 8 * (i >> 2));
;             if (BIAS == 1) s -= slope * (float)(dk < 0 ? -dk : dk);
;             if (BIAS == 2) { int d = dk < -256 ? -256 : (dk > 256 ? 256 : dk); s += rel[d + 256]; }
;             if (!FULL) { if (key < kbeg || key >= kend) s = -1e30f; }
;             st[kt][i] = s; mx = fmaxf(mx, s);
;         }
;     mx = fmaxf(mx, __shfl_xor(mx, 32));
;     const float mn = fmaxf(m, mx);
;     const float alpha = __builtin_amdgcn_exp2f((m - mn) * LOG2E);
;     m = mn;
;     float ps = 0.f;
; #pragma unroll
;     for (int kt = 0; kt < NKT; ++kt)
; #pragma unroll
;         for (int i = 0; i < 16; ++i) { const float pv = __builtin_amdgcn_exp2f((st[kt][i] - mn) * LOG2E); st[kt][i] = pv; ps += pv; }
;     l = l * alpha + ps;
	v_add_u32_e32 v160, 34, v120
	v_med3_i32 v160, v160, s45, v186
	v_lshl_add_u32 v160, v160, 2, s61
	ds_read_b32 v160, v160 offset:1024
	v_add_u32_e32 v161, 35, v120
	v_med3_i32 v161, v161, s45, v186
	v_lshl_add_u32 v161, v161, 2, s61
	ds_read_b32 v161, v161 offset:1024
	v_add_u32_e32 v162, 40, v120
	v_med3_i32 v162, v162, s45, v186
	v_lshl_add_u32 v162, v162, 2, s61
	ds_read_b32 v162, v162 offset:1024
	v_add_u32_e32 v163, 41, v120
	v_med3_i32 v163, v163, s45, v186
	v_lshl_add_u32 v163, v163, 2, s61
	ds_read_b32 v163, v163 offset:1024
	v_add_u32_e32 v164, 42, v120
	v_med3_i32 v164, v164, s45, v186
	v_lshl_add_u32 v164, v164, 2, s61
	ds_read_b32 v164, v164 offset:1024
	v_add_u32_e32 v165, 43, v120
	v_med3_i32 v165, v165, s45, v186
	v_lshl_add_u32 v165, v165, 2, s61
	ds_read_b32 v165, v165 offset:1024
	v_add_u32_e32 v166, 48, v120
	v_med3_i32 v166, v166, s45, v186
	v_lshl_add_u32 v166, v166, 2, s61
	ds_read_b32 v166, v166 offset:1024
	v_add_u32_e32 v167, 49, v120
	v_med3_i32 v167, v167, s45, v186
	v_lshl_add_u32 v167, v167, 2, s61
	ds_read_b32 v167, v167 offset:1024
	v_add_u32_e32 v168, 50, v120
	v_med3_i32 v168, v168, s45, v186
	v_lshl_add_u32 v168, v168, 2, s61
	ds_read_b32 v168, v168 offset:1024
	v_add_u32_e32 v169, 51, v120
	v_med3_i32 v169, v169, s45, v186
	v_lshl_add_u32 v169, v169, 2, s61
	ds_read_b32 v169, v169 offset:1024
	v_add_u32_e32 v170, 56, v120
	v_med3_i32 v170, v170, s45, v186
	v_lshl_add_u32 v170, v170, 2, s61
	ds_read_b32 v170, v170 offset:1024
	v_add_u32_e32 v171, 57, v120
	v_med3_i32 v171, v171, s45, v186
	v_lshl_add_u32 v171, v171, 2, s61
	ds_read_b32 v171, v171 offset:1024
	v_add_u32_e32 v172, 58, v120
	v_med3_i32 v172, v172, s45, v186
	v_lshl_add_u32 v172, v172, 2, s61
	ds_read_b32 v172, v172 offset:1024
	v_add_u32_e32 v173, 59, v120
	v_med3_i32 v173, v173, s45, v186
	v_lshl_add_u32 v173, v173, 2, s61
	ds_read_b32 v173, v173 offset:1024
.Lbf_s3_join:
	s_waitcnt lgkmcnt(0)
	v_cmp_lt_i32_e32 vcc, v188, v189
	v_add_f32_e32 v52, v52, v142
	s_add_u32 s0, s0, 0x10000
	s_addc_u32 s1, s1, 0
	v_add_u32_e32 v118, 64, v118
	s_cmp_eq_u32 s0, 0x80000
	v_add_f32_e32 v53, v53, v144
	v_add_f32_e32 v54, v54, v145
	v_add_f32_e32 v55, v55, v146
	v_add_f32_e32 v56, v56, v147
	v_add_f32_e32 v57, v57, v148
	v_add_f32_e32 v122, v58, v149
	v_add_f32_e32 v50, v50, v143
	v_add_f32_e32 v59, v59, v150
	v_add_f32_e32 v51, v51, v151
	v_add_f32_e32 v60, v60, v152
	v_max3_f32 v0, v50, s46, v51
	v_max3_f32 v0, v0, v52, v53
	v_max3_f32 v0, v0, v54, v55
	v_max3_f32 v0, v0, v56, v57
	v_add_f32_e32 v61, v61, v153
	v_max3_f32 v0, v0, v122, v59
	v_max3_f32 v0, v0, v60, v61
	v_add_f32_e32 v62, v62, v154
	v_add_f32_e32 v63, v63, v155
	v_max3_f32 v0, v0, v62, v63
	v_add_f32_e32 v64, v64, v156
	v_add_f32_e32 v65, v65, v157
	v_max3_f32 v0, v0, v64, v65
	v_add_f32_e32 v34, v34, v158
	v_add_f32_e32 v35, v35, v159
	v_max3_f32 v0, v0, v34, v35
	v_add_f32_e32 v36, v36, v160
	v_add_f32_e32 v37, v37, v161
	v_max3_f32 v0, v0, v36, v37
	v_add_f32_e32 v38, v38, v162
	v_add_f32_e32 v39, v39, v163
	v_max3_f32 v0, v0, v38, v39
	v_add_f32_e32 v40, v40, v164
	v_add_f32_e32 v41, v41, v165
	v_max3_f32 v0, v0, v40, v41
	v_add_f32_e32 v42, v42, v166
	v_add_f32_e32 v43, v43, v167
	v_max3_f32 v0, v0, v42, v43
	v_add_f32_e32 v44, v44, v168
	v_add_f32_e32 v45, v45, v169
	v_max3_f32 v0, v0, v44, v45
	v_add_f32_e32 v46, v46, v170
	v_add_f32_e32 v47, v47, v171
	v_max3_f32 v0, v0, v46, v47
	v_add_f32_e32 v48, v48, v172
	v_add_f32_e32 v49, v49, v173
	v_max3_f32 v58, v0, v48, v49
	v_cndmask_b32_e32 v0, v187, v188, vcc
	v_lshlrev_b32_e32 v0, 2, v0
	ds_bpermute_b32 v120, v0, v58
	s_waitcnt lgkmcnt(0)
	v_max3_f32 v58, v121, v58, v120
	v_sub_f32_e32 v50, v50, v58
	v_mul_f32_e32 v50, 0x3fb8aa3b, v50
	v_sub_f32_e32 v51, v51, v58
	v_exp_f32_e32 v50, v50
	v_mul_f32_e32 v51, 0x3fb8aa3b, v51
	v_sub_f32_e32 v52, v52, v58
	v_exp_f32_e32 v51, v51
	v_mul_f32_e32 v52, 0x3fb8aa3b, v52
	v_sub_f32_e32 v53, v53, v58
	v_sub_f32_e32 v35, v35, v58
	v_exp_f32_e32 v52, v52
	v_mul_f32_e32 v53, 0x3fb8aa3b, v53
	v_sub_f32_e32 v54, v54, v58
	v_mul_f32_e32 v35, 0x3fb8aa3b, v35
	v_exp_f32_e32 v53, v53
	v_mul_f32_e32 v54, 0x3fb8aa3b, v54
	v_sub_f32_e32 v55, v55, v58
	v_exp_f32_e32 v124, v35
	v_sub_f32_e32 v35, v36, v58
	v_sub_f32_e32 v120, v121, v58
	v_add_f32_e32 v121, 0, v50
	v_exp_f32_e32 v54, v54
	v_mul_f32_e32 v55, 0x3fb8aa3b, v55
	v_sub_f32_e32 v56, v56, v58
	v_mul_f32_e32 v35, 0x3fb8aa3b, v35
	v_add_f32_e32 v121, v51, v121
	v_exp_f32_e32 v55, v55
	v_mul_f32_e32 v56, 0x3fb8aa3b, v56
	v_sub_f32_e32 v57, v57, v58
	v_exp_f32_e32 v125, v35
	v_sub_f32_e32 v35, v37, v58
	v_add_f32_e32 v121, v52, v121
	v_exp_f32_e32 v56, v56
	v_mul_f32_e32 v57, 0x3fb8aa3b, v57
	v_sub_f32_e32 v122, v122, v58
	v_mul_f32_e32 v35, 0x3fb8aa3b, v35
	v_add_f32_e32 v121, v53, v121
	v_exp_f32_e32 v57, v57
	v_mul_f32_e32 v122, 0x3fb8aa3b, v122
	v_sub_f32_e32 v59, v59, v58
	v_exp_f32_e32 v126, v35
	v_sub_f32_e32 v35, v38, v58
	v_add_f32_e32 v121, v54, v121
	v_exp_f32_e32 v122, v122
	v_mul_f32_e32 v59, 0x3fb8aa3b, v59
	v_sub_f32_e32 v60, v60, v58
	v_mul_f32_e32 v35, 0x3fb8aa3b, v35
	v_add_f32_e32 v121, v55, v121
	v_exp_f32_e32 v123, v59
	v_mul_f32_e32 v60, 0x3fb8aa3b, v60
	v_sub_f32_e32 v61, v61, v58
	v_exp_f32_e32 v38, v35
	v_sub_f32_e32 v35, v39, v58
	v_add_f32_e32 v121, v56, v121
	v_exp_f32_e32 v60, v60
	v_mul_f32_e32 v61, 0x3fb8aa3b, v61
	v_sub_f32_e32 v62, v62, v58
	v_mul_f32_e32 v35, 0x3fb8aa3b, v35
	v_add_f32_e32 v121, v57, v121
	v_exp_f32_e32 v61, v61
	v_mul_f32_e32 v62, 0x3fb8aa3b, v62
; #define MFMA32(a, b, c) __builtin_amdgcn_mfma_f32_32x32x16_f16((a), (b), (c), 0, 0, 0)
; DI unsigned pk2(float lo, float hi) { f32x2 v = {lo, hi}; bf2_t b = __builtin_convertvector(v, bf2_t); return __builtin_bit_cast(unsigned, b); }
; template <int HD, int BIAS, bool FULL>
; DI void attn_block(const bf16_t* Kb, int ktb, const bf16_t* Vb, int vtb, int koff, int kpos0, int qp, float slope, const float* rel,
;                    const bf16x8 (&qf)[HD / 16], f32x16 (&o)[HD / 32], float& m, float& l) {
;     ...
;     const int kbeg = FULL ? 0 : koff, kend = FULL ? 64 : koff + 16;
;     const int s0 = FULL ? 0 : (koff >> 4);
;     int dq = kpos0 + 4 * h - qp; asm volatile("" : "+v"(dq));
;     bf16x8 kreg[NKT][KSQ];
; #pragma unroll
;     for (int kt = 0; kt < NKT; ++kt)
; #pragma unroll
;         for (int ks = 0; ks < KSQ; ++ks) kreg[kt][ks] = *(const bf16x8*)(Kb + (size_t)kt * ktb + ks * 512 + lane * 8);
;     ...
; #pragma unroll
;     for (int kt = 0; kt < NKT; ++kt)
; #pragma unroll
;         for (int i = 0; i < 16; ++i) { const float pv = __builtin_amdgcn_exp2f((st[kt][i] - mn) * LOG2E); st[kt][i] = pv; ps += pv; }
;     l = l * alpha + ps;
; #pragma unroll
;     for (int dt = 0; dt < DT; ++dt)
; #pragma unroll
;         for (int i = 0; i < 16; ++i) o[dt][i] *= alpha;
; #pragma unroll
;     for (int si = 0; si < NS; ++si) {
;         u32x4 pw;
;         if (FULL) { const int kt = si >> 1, b0 = (si & 1) * 8; pw = (u32x4){pk2(st[kt][b0], st[kt][b0 + 1]), pk2(st[kt][b0 + 2], st[kt][b0 + 3]), pk2(st[kt][b0 + 4], st[kt][b0 + 5]), pk2(st[kt][b0 + 6], st[kt][b0 + 7])}; }
;         else {
;             const u32x4 lo = {pk2(st[0][0], st[0][1]), pk2(st[0][2], st[0][3]), pk2(st[0][4], st[0][5]), pk2(st[0][6], st[0][7])};
;             const u32x4 hi = {pk2(st[0][8], st[0][9]), pk2(st[0][10], st[0][11]), pk2(st[0][12], st[0][13]), pk2(st[0][14], st[0][15])};
;             pw = (s0 & 1) ? hi : lo;
;         }
;         const bf16x8 pf = __builtin_bit_cast(bf16x8, pw);
; #pragma unroll
;         for (int dt = 0; dt < DT; ++dt) o[dt] = MFMA32(vreg[dt][si], pf, o[dt]);
;     }
; }
	v_sub_f32_e32 v63, v63, v58
	v_exp_f32_e32 v39, v35
	v_sub_f32_e32 v35, v40, v58
	v_add_f32_e32 v121, v122, v121
	v_exp_f32_e32 v62, v62
	v_mul_f32_e32 v63, 0x3fb8aa3b, v63
	v_sub_f32_e32 v64, v64, v58
	v_mul_f32_e32 v35, 0x3fb8aa3b, v35
	v_add_f32_e32 v59, v123, v121
	v_exp_f32_e32 v63, v63
	v_mul_f32_e32 v64, 0x3fb8aa3b, v64
	v_sub_f32_e32 v65, v65, v58
	v_exp_f32_e32 v40, v35
	v_sub_f32_e32 v35, v41, v58
	v_add_f32_e32 v59, v60, v59
	v_exp_f32_e32 v64, v64
	v_mul_f32_e32 v65, 0x3fb8aa3b, v65
	v_sub_f32_e32 v34, v34, v58
	v_mul_f32_e32 v35, 0x3fb8aa3b, v35
	v_add_f32_e32 v59, v61, v59
	v_exp_f32_e32 v65, v65
	v_mul_f32_e32 v34, 0x3fb8aa3b, v34
	v_exp_f32_e32 v41, v35
	v_sub_f32_e32 v35, v42, v58
	v_add_f32_e32 v59, v62, v59
	v_exp_f32_e32 v121, v34
	v_mul_f32_e32 v35, 0x3fb8aa3b, v35
	v_add_f32_e32 v59, v63, v59
	v_exp_f32_e32 v42, v35
	v_sub_f32_e32 v35, v43, v58
	v_add_f32_e32 v59, v64, v59
	v_mul_f32_e32 v35, 0x3fb8aa3b, v35
	v_add_f32_e32 v59, v65, v59
	v_exp_f32_e32 v43, v35
	v_sub_f32_e32 v35, v44, v58
	v_add_f32_e32 v34, v121, v59
	v_mul_f32_e32 v35, 0x3fb8aa3b, v35
	v_add_f32_e32 v34, v124, v34
	v_exp_f32_e32 v44, v35
	v_sub_f32_e32 v35, v45, v58
	v_add_f32_e32 v34, v125, v34
	v_mul_f32_e32 v35, 0x3fb8aa3b, v35
	v_add_f32_e32 v34, v126, v34
	v_exp_f32_e32 v45, v35
	v_sub_f32_e32 v35, v46, v58
	v_add_f32_e32 v34, v38, v34
	v_mul_f32_e32 v35, 0x3fb8aa3b, v35
	v_add_f32_e32 v34, v39, v34
	v_exp_f32_e32 v46, v35
	v_sub_f32_e32 v35, v47, v58
	v_add_f32_e32 v34, v40, v34
	v_mul_f32_e32 v35, 0x3fb8aa3b, v35
	v_add_f32_e32 v34, v41, v34
	v_exp_f32_e32 v47, v35
	v_sub_f32_e32 v35, v48, v58
	v_add_f32_e32 v34, v42, v34
	v_mul_f32_e32 v35, 0x3fb8aa3b, v35
	v_add_f32_e32 v34, v43, v34
	v_exp_f32_e32 v48, v35
	v_sub_f32_e32 v35, v49, v58
	v_add_f32_e32 v34, v44, v34
	v_mul_f32_e32 v35, 0x3fb8aa3b, v35
	v_add_f32_e32 v34, v45, v34
	v_exp_f32_e32 v49, v35
	v_add_f32_e32 v34, v46, v34
	v_add_f32_e32 v34, v47, v34
	v_mul_f32_e32 v120, 0x3fb8aa3b, v120
	v_add_f32_e32 v34, v48, v34
	v_add_f32_e32 v59, v49, v34
	v_exp_f32_e32 v34, v120
	v_cvt_pk_f16_f32 v36, v54, v55
	v_cvt_pk_f16_f32 v37, v56, v57
	v_fmac_f32_e32 v59, v119, v34
	v_pk_mul_f32 v[2:3], v[2:3], v[34:35] op_sel_hi:[1,0]
	v_pk_mul_f32 v[4:5], v[4:5], v[34:35] op_sel_hi:[1,0]
	v_pk_mul_f32 v[6:7], v[6:7], v[34:35] op_sel_hi:[1,0]
	v_pk_mul_f32 v[8:9], v[8:9], v[34:35] op_sel_hi:[1,0]
	v_pk_mul_f32 v[10:11], v[10:11], v[34:35] op_sel_hi:[1,0]
	v_pk_mul_f32 v[12:13], v[12:13], v[34:35] op_sel_hi:[1,0]
	v_pk_mul_f32 v[14:15], v[14:15], v[34:35] op_sel_hi:[1,0]
	v_pk_mul_f32 v[16:17], v[16:17], v[34:35] op_sel_hi:[1,0]
	v_pk_mul_f32 v[18:19], v[18:19], v[34:35] op_sel_hi:[1,0]
	v_pk_mul_f32 v[20:21], v[20:21], v[34:35] op_sel_hi:[1,0]
	v_pk_mul_f32 v[22:23], v[22:23], v[34:35] op_sel_hi:[1,0]
	v_pk_mul_f32 v[24:25], v[24:25], v[34:35] op_sel_hi:[1,0]
	v_pk_mul_f32 v[26:27], v[26:27], v[34:35] op_sel_hi:[1,0]
	v_pk_mul_f32 v[28:29], v[28:29], v[34:35] op_sel_hi:[1,0]
	v_pk_mul_f32 v[30:31], v[30:31], v[34:35] op_sel_hi:[1,0]
	v_pk_mul_f32 v[32:33], v[32:33], v[34:35] op_sel_hi:[1,0]
	v_cvt_pk_f16_f32 v34, v50, v51
	v_cvt_pk_f16_f32 v35, v52, v53
	s_waitcnt vmcnt(7)
	s_nop 0
	v_mfma_f32_32x32x16_f16 v[2:17], v[110:113], v[34:37], v[2:17]
	s_waitcnt vmcnt(5)
	v_mfma_f32_32x32x16_f16 v[18:33], v[106:109], v[34:37], v[18:33]
	v_cvt_pk_f16_f32 v34, v122, v123
	v_cvt_pk_f16_f32 v35, v60, v61
	v_cvt_pk_f16_f32 v36, v62, v63
	v_cvt_pk_f16_f32 v37, v64, v65
	s_nop 1
	v_mfma_f32_32x32x16_f16 v[2:17], v[102:105], v[34:37], v[2:17]
	s_waitcnt vmcnt(4)
	v_mfma_f32_32x32x16_f16 v[18:33], v[98:101], v[34:37], v[18:33]
	v_cvt_pk_f16_f32 v34, v121, v124
	v_cvt_pk_f16_f32 v35, v125, v126
	v_cvt_pk_f16_f32 v36, v38, v39
	v_cvt_pk_f16_f32 v37, v40, v41
	s_waitcnt vmcnt(3)
	s_nop 0
	v_mfma_f32_32x32x16_f16 v[2:17], v[94:97], v[34:37], v[2:17]
	s_waitcnt vmcnt(1)
	v_mfma_f32_32x32x16_f16 v[18:33], v[90:93], v[34:37], v[18:33]
	v_cvt_pk_f16_f32 v34, v42, v43
	v_cvt_pk_f16_f32 v35, v44, v45
	v_cvt_pk_f16_f32 v36, v46, v47
	v_cvt_pk_f16_f32 v37, v48, v49
	s_nop 1
	v_mfma_f32_32x32x16_f16 v[2:17], v[86:89], v[34:37], v[2:17]
	s_waitcnt vmcnt(0)
	v_mfma_f32_32x32x16_f16 v[18:33], v[82:85], v[34:37], v[18:33]
	s_cbranch_scc0 .LBB0_329
	v_mov_b32_e32 v34, v176
	s_lshl_b32 s0, s96, 10
	v_lshrrev_b32_e32 v35, 3, v34
	v_and_b32_e32 v63, 4, v35
	v_or_b32_e32 v35, s97, v117
	v_lshlrev_b32_e32 v34, 4, v34
	v_sub_u32_e32 v62, v63, v35
	v_and_b32_e32 v38, 0x3f0, v34
	global_load_dwordx4 v[34:37], v38, s[66:67]
	global_load_dwordx4 v[82:85], v38, s[66:67] offset:1024
	global_load_dwordx4 v[86:89], v38, s[66:67] offset:2048
	global_load_dwordx4 v[90:93], v38, s[66:67] offset:3072
	s_add_u32 s0, s57, s0
	s_addc_u32 s1, s60, 0
	global_load_dwordx4 v[50:53], v38, s[0:1]
	global_load_dwordx4 v[54:57], v38, s[0:1] offset:2048
	s_waitcnt vmcnt(5)
	v_mfma_f32_32x32x16_f16 v[34:49], v[34:37], v[78:81], 0
	s_waitcnt vmcnt(4)
	v_mfma_f32_32x32x16_f16 v[34:49], v[82:85], v[74:77], v[34:49]
	s_waitcnt vmcnt(3)
	v_mfma_f32_32x32x16_f16 v[34:49], v[86:89], v[66:69], v[34:49]
	s_waitcnt vmcnt(2)
	v_mfma_f32_32x32x16_f16 v[34:49], v[90:93], v[70:73], v[34:49]
	v_cmp_gt_u32_e64 s[0:1], s97, v63
	v_cmp_le_u32_e32 vcc, s97, v63
	v_mov_b32_e32 v60, 0xf149f2ca
	v_mov_b32_e32 v61, 0xf149f2ca
	s_and_saveexec_b64 s[2:3], vcc
	s_cbranch_execz .LBB0_332
	v_med3_i32 v61, v62, s45, v186
	v_lshl_add_u32 v61, v61, 2, s61
	ds_read_b32 v61, v61 offset:1024
	s_waitcnt lgkmcnt(0)
	s_nop 1
	v_add_f32_e32 v61, v34, v61

; #define MFMA32(a, b, c) __builtin_amdgcn_mfma_f32_32x32x16_f16((a), (b), (c), 0, 0, 0)
; DI int crow(int i, int h) { return (i & 3) + 8 * (i >> 2) + 4 * h; }
; template <int HD, int BIAS, bool FULL>
; DI void attn_block(const bf16_t* Kb, int ktb, const bf16_t* Vb, int vtb, int koff, int kpos0, int qp, float slope, const float* rel,
;                    const bf16x8 (&qf)[HD / 16], f32x16 (&o)[HD / 32], float& m, float& l) {
;     ...
;     bf16x8 kreg[NKT][KSQ];
; #pragma unroll
;     for (int kt = 0; kt < NKT; ++kt)
; #pragma unroll
;         for (int ks = 0; ks < KSQ; ++ks) kreg[kt][ks] = *(const bf16x8*)(Kb + (size_t)kt * ktb + ks * 512 + lane * 8);
;     constexpr int NS = FULL ? 4 : 1;
;     bf16x8 vreg[DT][NS];
;     auto loadV = [&]() {
; #pragma unroll
;         for (int si = 0; si < NS; ++si)
; #pragma unroll
;             for (int dt = 0; dt < DT; ++dt) { const int s = FULL ? si : s0; vreg[dt][si] = *(const bf16x8*)(Vb + (size_t)(s >> 1) * vtb + dt * 1024 + (s & 1) * 512 + lane * 8); }
;     };
;     if (VTOP) loadV();
;     __builtin_amdgcn_sched_barrier(0);
;     f32x16 st[NKT];
; #pragma unroll
;     for (int kt = 0; kt < NKT; ++kt) {
; #pragma unroll
;         for (int i = 0; i < 16; ++i) st[kt][i] = 0.f;
; #pragma unroll
;         for (int ks = 0; ks < KSQ; ++ks) st[kt] = MFMA32(kreg[kt][ks], qf[ks], st[kt]);
;     }
;     __builtin_amdgcn_sched_barrier(0);
;     if (!VTOP) loadV();
;     float mx = -1e30f;
; #pragma unroll
;     for (int kt = 0; kt < NKT; ++kt)
; #pragma unroll
;         for (int i = 0; i < 16; ++i) {
;             const int key = kt * 32 + crow(i, h);
;             float s = st[kt][i];
;             const int dk = dq + (kt * 32 + (i & 3) + 8 * (i >> 2));
;             if (BIAS == 1) s -= slope * (float)(dk < 0 ? -dk : dk);
;             if (BIAS == 2) { int d = dk < -256 ? -256 : (dk > 256 ? 256 : dk); s += rel[d + 256]; }
.LBB0_362:
	v_mov_b32_e32 v0, v176
	s_mov_b32 s29, 0x1020000
	v_lshrrev_b32_e32 v34, 3, v0
	v_and_b32_e32 v0, 63, v0
	v_and_b32_e32 v34, 4, v34
	v_lshlrev_b32_e32 v0, 4, v0
	s_waitcnt vmcnt(4)
	v_add_u32_e32 v120, v115, v34
	v_lshl_add_u64 v[34:35], s[0:1], 0, v[0:1]
	v_add_co_u32_e32 v50, vcc, s22, v34
	global_load_dwordx4 v[38:41], v0, s[0:1]
	global_load_dwordx4 v[42:45], v0, s[0:1] offset:1024
	global_load_dwordx4 v[46:49], v0, s[0:1] offset:2048
	global_load_dwordx4 v[122:125], v0, s[0:1] offset:3072
	v_addc_co_u32_e32 v51, vcc, 0, v35, vcc
	global_load_dwordx4 v[126:129], v[50:51], off
	global_load_dwordx4 v[130:133], v[50:51], off offset:1024
	global_load_dwordx4 v[134:137], v[50:51], off offset:2048
	global_load_dwordx4 v[138:141], v[50:51], off offset:3072
	v_add_co_u32_e32 v50, vcc, s29, v34
	s_mov_b32 s29, 0x1028000
	s_nop 0
	v_addc_co_u32_e32 v51, vcc, 0, v35, vcc
	v_add_co_u32_e32 v34, vcc, s29, v34
	global_load_dwordx4 v[102:105], v[50:51], off
	global_load_dwordx4 v[90:93], v[50:51], off offset:1024
	global_load_dwordx4 v[110:113], v[50:51], off offset:2048
	global_load_dwordx4 v[94:97], v[50:51], off offset:3072
	v_addc_co_u32_e32 v35, vcc, 0, v35, vcc
	global_load_dwordx4 v[98:101], v[34:35], off
	global_load_dwordx4 v[82:85], v[34:35], off offset:1024
	global_load_dwordx4 v[106:109], v[34:35], off offset:2048
	global_load_dwordx4 v[86:89], v[34:35], off offset:3072
	v_mov_b32_e32 v119, v36
	s_waitcnt vmcnt(15)
	v_mfma_f32_32x32x16_f16 v[50:65], v[38:41], v[66:69], 0
	s_waitcnt vmcnt(14)
	v_mfma_f32_32x32x16_f16 v[50:65], v[42:45], v[70:73], v[50:65]
	s_waitcnt vmcnt(13)
	v_mfma_f32_32x32x16_f16 v[50:65], v[46:49], v[74:77], v[50:65]
	s_waitcnt vmcnt(11)
	v_mfma_f32_32x32x16_f16 v[34:49], v[126:129], v[66:69], 0
	s_waitcnt vmcnt(10)
	v_mfma_f32_32x32x16_f16 v[34:49], v[130:133], v[70:73], v[34:49]
	s_waitcnt vmcnt(9)
	v_mfma_f32_32x32x16_f16 v[34:49], v[134:137], v[74:77], v[34:49]
	s_waitcnt vmcnt(8)
	v_mfma_f32_32x32x16_f16 v[34:49], v[138:141], v[78:81], v[34:49]
	v_mfma_f32_32x32x16_f16 v[50:65], v[122:125], v[78:81], v[50:65]
	v_cmp_lt_i32_e32 vcc, 0xfffffec5, v120
	s_cbranch_vccnz .Lbf_p3_slow
	v_mov_b32_e32 v142, s3
	ds_read_b32 v143, v142
	ds_read_b32 v144, v142
	ds_read_b32 v145, v142
	ds_read_b32 v146, v142
	ds_read_b32 v147, v142
	ds_read_b32 v148, v142
	ds_read_b32 v149, v142
	ds_read_b32 v150, v142
	ds_read_b32 v151, v142
	ds_read_b32 v152, v142
	ds_read_b32 v153, v142
	ds_read_b32 v154, v142
	ds_read_b32 v155, v142
	ds_read_b32 v156, v142
	ds_read_b32 v157, v142
	ds_read_b32 v158, v142
	ds_read_b32 v159, v142
	ds_read_b32 v160, v142
	ds_read_b32 v161, v142
	ds_read_b32 v162, v142
	ds_read_b32 v163, v142
	ds_read_b32 v164, v142
	ds_read_b32 v165, v142
	ds_read_b32 v166, v142
	ds_read_b32 v167, v142
	ds_read_b32 v168, v142
	ds_read_b32 v169, v142
	ds_read_b32 v170, v142
	ds_read_b32 v171, v142
	ds_read_b32 v172, v142
	ds_read_b32 v173, v142
	ds_read_b32 v142, v142
	s_branch .Lbf_p3_join
.Lbf_p3_slow:
	v_add_u32_e32 v142, 2, v120
	v_med3_i32 v142, v142, s45, v186
	v_lshl_add_u32 v142, v142, 2, s3
	ds_read_b32 v142, v142 offset:1024
	v_med3_i32 v143, v120, s45, v186
	v_lshl_add_u32 v143, v143, 2, s3
	ds_read_b32 v143, v143 offset:1024
	v_add_u32_e32 v144, 3, v120
	v_med3_i32 v144, v144, s45, v186
	v_lshl_add_u32 v144, v144, 2, s3
	ds_read_b32 v144, v144 offset:1024
	v_add_u32_e32 v145, 8, v120
	v_med3_i32 v145, v145, s45, v186
	v_lshl_add_u32 v145, v145, 2, s3
	ds_read_b32 v145, v145 offset:1024
	v_add_u32_e32 v146, 9, v120
	v_med3_i32 v146, v146, s45, v186
	v_lshl_add_u32 v146, v146, 2, s3
	ds_read_b32 v146, v146 offset:1024
	v_add_u32_e32 v147, 10, v120
	v_med3_i32 v147, v147, s45, v186
	v_lshl_add_u32 v147, v147, 2, s3
	ds_read_b32 v147, v147 offset:1024
	v_add_u32_e32 v148, 11, v120
	v_med3_i32 v148, v148, s45, v186
	v_lshl_add_u32 v148, v148, 2, s3
	ds_read_b32 v148, v148 offset:1024
	v_add_u32_e32 v149, 16, v120
	v_med3_i32 v149, v149, s45, v186
	v_lshl_add_u32 v149, v149, 2, s3
	ds_read_b32 v149, v149 offset:1024
	v_add_u32_e32 v150, 17, v120
	v_med3_i32 v150, v150, s45, v186
	v_lshl_add_u32 v150, v150, 2, s3
	ds_read_b32 v150, v150 offset:1024
	v_add_u32_e32 v151, 18, v120
	v_med3_i32 v151, v151, s45, v186
	v_lshl_add_u32 v151, v151, 2, s3
	ds_read_b32 v151, v151 offset:1024
	v_add_u32_e32 v152, 19, v120
	v_med3_i32 v152, v152, s45, v186
	v_lshl_add_u32 v152, v152, 2, s3
	ds_read_b32 v152, v152 offset:1024
	v_add_u32_e32 v153, 24, v120
	v_med3_i32 v153, v153, s45, v186
	v_lshl_add_u32 v153, v153, 2, s3
	ds_read_b32 v153, v153 offset:1024
	v_add_u32_e32 v154, 25, v120
	v_med3_i32 v154, v154, s45, v186
	v_lshl_add_u32 v154, v154, 2, s3
	ds_read_b32 v154, v154 offset:1024
	v_add_u32_e32 v155, 26, v120
	v_med3_i32 v155, v155, s45, v186
	v_lshl_add_u32 v155, v155, 2, s3
	ds_read_b32 v155, v155 offset:1024
	v_add_u32_e32 v156, 27, v120
	v_med3_i32 v156, v156, s45, v186
	v_lshl_add_u32 v156, v156, 2, s3
	ds_read_b32 v156, v156 offset:1024
	v_add_u32_e32 v157, 32, v120
	v_med3_i32 v157, v157, s45, v186
	v_lshl_add_u32 v157, v157, 2, s3
	ds_read_b32 v157, v157 offset:1024
	v_add_u32_e32 v158, 33, v120
	v_med3_i32 v158, v158, s45, v186
	v_lshl_add_u32 v158, v158, 2, s3
	ds_read_b32 v158, v158 offset:1024
	v_add_u32_e32 v159, 1, v120
	v_med3_i32 v159, v159, s45, v186
	v_lshl_add_u32 v159, v159, 2, s3
	v_add_u32_e32 v160, 34, v120
	v_med3_i32 v160, v160, s45, v186
	v_lshl_add_u32 v160, v160, 2, s3
	ds_read_b32 v159, v159 offset:1024
	ds_read_b32 v160, v160 offset:1024
	v_add_u32_e32 v161, 35, v120
	v_med3_i32 v161, v161, s45, v186
	v_lshl_add_u32 v161, v161, 2, s3
	ds_read_b32 v161, v161 offset:1024
; DI int crow(int i, int h) { return (i & 3) + 8 * (i >> 2) + 4 * h; }
; template <int HD, int BIAS, bool FULL>
; DI void attn_block(const bf16_t* Kb, int ktb, const bf16_t* Vb, int vtb, int koff, int kpos0, int qp, float slope, const float* rel,
;                    const bf16x8 (&qf)[HD / 16], f32x16 (&o)[HD / 32], float& m, float& l) {
;     ...
;     for (int kt = 0; kt < NKT; ++kt)
; #pragma unroll
;         for (int i = 0; i < 16; ++i) {
;             const int key = kt * 32 + crow(i, h);
;             float s = st[kt][i];
;             const int dk = dq + (kt * 32 + (i & 3) + 8 * (i >> 2));
;             if (BIAS == 1) s -= slope * (float)(dk < 0 ? -dk : dk);
;             if (BIAS == 2) { int d = dk < -256 ? -256 : (dk > 256 ? 256 : dk); s += rel[d + 256]; }
;             if (!FULL) { if (key < kbeg || key >= kend) s = -1e30f; }
;             st[kt][i] = s; mx = fmaxf(mx, s);
;         }
;     mx = fmaxf(mx, __shfl_xor(mx, 32));
	v_add_u32_e32 v162, 40, v120
	v_med3_i32 v162, v162, s45, v186
	v_lshl_add_u32 v162, v162, 2, s3
	ds_read_b32 v162, v162 offset:1024
	v_add_u32_e32 v163, 41, v120
	v_med3_i32 v163, v163, s45, v186
	v_lshl_add_u32 v163, v163, 2, s3
	ds_read_b32 v163, v163 offset:1024
	v_add_u32_e32 v164, 42, v120
	v_med3_i32 v164, v164, s45, v186
	v_lshl_add_u32 v164, v164, 2, s3
	ds_read_b32 v164, v164 offset:1024
	v_add_u32_e32 v165, 43, v120
	v_med3_i32 v165, v165, s45, v186
	v_lshl_add_u32 v165, v165, 2, s3
	ds_read_b32 v165, v165 offset:1024
	v_add_u32_e32 v166, 48, v120
	v_med3_i32 v166, v166, s45, v186
	v_lshl_add_u32 v166, v166, 2, s3
	ds_read_b32 v166, v166 offset:1024
	v_add_u32_e32 v167, 49, v120
	v_med3_i32 v167, v167, s45, v186
	v_lshl_add_u32 v167, v167, 2, s3
	ds_read_b32 v167, v167 offset:1024
	v_add_u32_e32 v168, 50, v120
	v_med3_i32 v168, v168, s45, v186
	v_lshl_add_u32 v168, v168, 2, s3
	ds_read_b32 v168, v168 offset:1024
	v_add_u32_e32 v169, 51, v120
	v_med3_i32 v169, v169, s45, v186
	v_lshl_add_u32 v169, v169, 2, s3
	ds_read_b32 v169, v169 offset:1024
	v_add_u32_e32 v170, 56, v120
	v_med3_i32 v170, v170, s45, v186
	v_lshl_add_u32 v170, v170, 2, s3
	ds_read_b32 v170, v170 offset:1024
	v_add_u32_e32 v171, 57, v120
	v_med3_i32 v171, v171, s45, v186
	v_lshl_add_u32 v171, v171, 2, s3
	ds_read_b32 v171, v171 offset:1024
	v_add_u32_e32 v172, 58, v120
	v_med3_i32 v172, v172, s45, v186
	v_lshl_add_u32 v172, v172, 2, s3
	ds_read_b32 v172, v172 offset:1024
	v_add_u32_e32 v173, 59, v120
	v_med3_i32 v173, v173, s45, v186
	v_lshl_add_u32 v173, v173, 2, s3
	ds_read_b32 v173, v173 offset:1024
.Lbf_p3_join:
	s_waitcnt lgkmcnt(0)
	s_add_i32 s28, s28, 1
	s_nop 2
	v_add_f32_e32 v52, v52, v142
	s_add_u32 s0, s0, 0x10000
	s_addc_u32 s1, s1, 0
	v_add_u32_e32 v115, 64, v115
	s_cmp_lg_u32 s73, s28
	v_add_f32_e32 v53, v53, v144
	v_add_f32_e32 v54, v54, v145
	v_add_f32_e32 v55, v55, v146
	v_add_f32_e32 v56, v56, v147
	v_add_f32_e32 v57, v57, v148
	v_add_f32_e32 v58, v58, v149
	v_add_f32_e32 v59, v59, v150
	v_add_f32_e32 v60, v60, v151
	v_add_f32_e32 v61, v61, v152
	v_add_f32_e32 v62, v62, v153
	v_add_f32_e32 v63, v63, v154
	v_add_f32_e32 v64, v64, v155
	v_add_f32_e32 v65, v65, v156
	v_add_f32_e32 v121, v34, v157
	v_add_f32_e32 v50, v50, v143
	v_add_f32_e32 v122, v35, v158
	v_add_f32_e32 v51, v51, v159
	v_add_f32_e32 v36, v36, v160
	v_max3_f32 v0, v50, s46, v51
	v_max3_f32 v0, v0, v52, v53
	v_max3_f32 v0, v0, v54, v55
	v_max3_f32 v0, v0, v56, v57
	v_add_f32_e32 v123, v37, v161
	v_max3_f32 v0, v0, v58, v59
	v_max3_f32 v0, v0, v60, v61
	v_max3_f32 v0, v0, v62, v63
	v_max3_f32 v0, v0, v64, v65
	v_add_f32_e32 v38, v38, v162
	v_max3_f32 v0, v0, v121, v122
	v_max3_f32 v0, v0, v36, v123
	v_add_f32_e32 v39, v39, v163
	v_max3_f32 v0, v0, v38, v39
	v_add_f32_e32 v40, v40, v164
	v_add_f32_e32 v41, v41, v165
	v_max3_f32 v0, v0, v40, v41
	v_add_f32_e32 v42, v42, v166
	v_add_f32_e32 v43, v43, v167
	v_max3_f32 v0, v0, v42, v43
	v_add_f32_e32 v44, v44, v168
	v_add_f32_e32 v45, v45, v169
	v_max3_f32 v0, v0, v44, v45
	v_add_f32_e32 v46, v46, v170
	v_add_f32_e32 v47, v47, v171
	v_max3_f32 v0, v0, v46, v47
	v_add_f32_e32 v48, v48, v172
	v_add_f32_e32 v49, v49, v173
	v_max3_f32 v37, v0, v48, v49
	v_mbcnt_hi_u32_b32 v0, -1, v178
	v_and_b32_e32 v35, 64, v0
	v_xor_b32_e32 v34, 32, v0
	v_add_u32_e32 v35, 64, v35
	v_cmp_lt_i32_e32 vcc, v34, v35
	s_nop 1
	v_cndmask_b32_e32 v120, v0, v34, vcc
	v_lshlrev_b32_e32 v120, 2, v120
	ds_bpermute_b32 v120, v120, v37
	s_waitcnt lgkmcnt(0)
; #define MFMA32(a, b, c) __builtin_amdgcn_mfma_f32_32x32x16_f16((a), (b), (c), 0, 0, 0)
; DI unsigned pk2(float lo, float hi) { f32x2 v = {lo, hi}; bf2_t b = __builtin_convertvector(v, bf2_t); return __builtin_bit_cast(unsigned, b); }
; template <int HD, int BIAS, bool FULL>
; DI void attn_block(const bf16_t* Kb, int ktb, const bf16_t* Vb, int vtb, int koff, int kpos0, int qp, float slope, const float* rel,
;                    const bf16x8 (&qf)[HD / 16], f32x16 (&o)[HD / 32], float& m, float& l) {
;     ...
;     mx = fmaxf(mx, __shfl_xor(mx, 32));
;     const float mn = fmaxf(m, mx);
;     const float alpha = __builtin_amdgcn_exp2f((m - mn) * LOG2E);
;     m = mn;
;     float ps = 0.f;
; #pragma unroll
;     for (int kt = 0; kt < NKT; ++kt)
; #pragma unroll
;         for (int i = 0; i < 16; ++i) { const float pv = __builtin_amdgcn_exp2f((st[kt][i] - mn) * LOG2E); st[kt][i] = pv; ps += pv; }
;     l = l * alpha + ps;
; #pragma unroll
;     for (int dt = 0; dt < DT; ++dt)
; #pragma unroll
;         for (int i = 0; i < 16; ++i) o[dt][i] *= alpha;
; #pragma unroll
;     for (int si = 0; si < NS; ++si) {
;         u32x4 pw;
;         if (FULL) { const int kt = si >> 1, b0 = (si & 1) * 8; pw = (u32x4){pk2(st[kt][b0], st[kt][b0 + 1]), pk2(st[kt][b0 + 2], st[kt][b0 + 3]), pk2(st[kt][b0 + 4], st[kt][b0 + 5]), pk2(st[kt][b0 + 6], st[kt][b0 + 7])}; }
;         else {
;             const u32x4 lo = {pk2(st[0][0], st[0][1]), pk2(st[0][2], st[0][3]), pk2(st[0][4], st[0][5]), pk2(st[0][6], st[0][7])};
;             const u32x4 hi = {pk2(st[0][8], st[0][9]), pk2(st[0][10], st[0][11]), pk2(st[0][12], st[0][13]), pk2(st[0][14], st[0][15])};
;             pw = (s0 & 1) ? hi : lo;
;         }
;         const bf16x8 pf = __builtin_bit_cast(bf16x8, pw);
; #pragma unroll
;         for (int dt = 0; dt < DT; ++dt) o[dt] = MFMA32(vreg[dt][si], pf, o[dt]);
;     }
; }
	v_max3_f32 v37, v118, v37, v120
	v_sub_f32_e32 v50, v50, v37
	v_mul_f32_e32 v50, 0x3fb8aa3b, v50
	v_sub_f32_e32 v51, v51, v37
	v_exp_f32_e32 v50, v50
	v_mul_f32_e32 v51, 0x3fb8aa3b, v51
	v_sub_f32_e32 v52, v52, v37
	v_exp_f32_e32 v51, v51
	v_mul_f32_e32 v52, 0x3fb8aa3b, v52
	v_sub_f32_e32 v53, v53, v37
	v_exp_f32_e32 v52, v52
	v_mul_f32_e32 v53, 0x3fb8aa3b, v53
	v_sub_f32_e32 v54, v54, v37
	v_exp_f32_e32 v53, v53
	v_mul_f32_e32 v54, 0x3fb8aa3b, v54
	v_sub_f32_e32 v55, v55, v37
	v_add_f32_e32 v120, 0, v50
	v_exp_f32_e32 v54, v54
	v_mul_f32_e32 v55, 0x3fb8aa3b, v55
	v_sub_f32_e32 v56, v56, v37
	v_add_f32_e32 v120, v51, v120
	v_exp_f32_e32 v55, v55
	v_mul_f32_e32 v56, 0x3fb8aa3b, v56
	v_sub_f32_e32 v57, v57, v37
	v_add_f32_e32 v120, v52, v120
	v_exp_f32_e32 v56, v56
	v_mul_f32_e32 v57, 0x3fb8aa3b, v57
	v_sub_f32_e32 v58, v58, v37
	v_add_f32_e32 v120, v53, v120
	v_exp_f32_e32 v57, v57
	v_mul_f32_e32 v58, 0x3fb8aa3b, v58
	v_sub_f32_e32 v59, v59, v37
	v_add_f32_e32 v120, v54, v120
	v_exp_f32_e32 v58, v58
	v_mul_f32_e32 v59, 0x3fb8aa3b, v59
	v_sub_f32_e32 v60, v60, v37
	v_add_f32_e32 v120, v55, v120
	v_exp_f32_e32 v59, v59
	v_mul_f32_e32 v60, 0x3fb8aa3b, v60
	v_sub_f32_e32 v61, v61, v37
	v_add_f32_e32 v120, v56, v120
	v_exp_f32_e32 v60, v60
	v_mul_f32_e32 v61, 0x3fb8aa3b, v61
	v_sub_f32_e32 v62, v62, v37
	v_add_f32_e32 v120, v57, v120
	v_exp_f32_e32 v61, v61
	v_mul_f32_e32 v62, 0x3fb8aa3b, v62
	v_sub_f32_e32 v63, v63, v37
	v_add_f32_e32 v120, v58, v120
	v_exp_f32_e32 v62, v62
	v_mul_f32_e32 v63, 0x3fb8aa3b, v63
	v_sub_f32_e32 v64, v64, v37
	v_add_f32_e32 v120, v59, v120
	v_exp_f32_e32 v63, v63
	v_mul_f32_e32 v64, 0x3fb8aa3b, v64
	v_sub_f32_e32 v65, v65, v37
	v_add_f32_e32 v120, v60, v120
	v_exp_f32_e32 v64, v64
	v_mul_f32_e32 v65, 0x3fb8aa3b, v65
	v_sub_f32_e32 v121, v121, v37
	v_add_f32_e32 v120, v61, v120
	v_exp_f32_e32 v65, v65
	v_mul_f32_e32 v121, 0x3fb8aa3b, v121
	v_sub_f32_e32 v122, v122, v37
	v_add_f32_e32 v120, v62, v120
	v_exp_f32_e32 v121, v121
	v_mul_f32_e32 v122, 0x3fb8aa3b, v122
	v_sub_f32_e32 v36, v36, v37
	v_add_f32_e32 v120, v63, v120
	v_exp_f32_e32 v122, v122
	v_mul_f32_e32 v36, 0x3fb8aa3b, v36
	v_add_f32_e32 v120, v64, v120
	v_exp_f32_e32 v124, v36
	v_add_f32_e32 v120, v65, v120
	v_add_f32_e32 v120, v121, v120
	v_sub_f32_e32 v38, v38, v37
	v_add_f32_e32 v120, v122, v120
	v_mul_f32_e32 v38, 0x3fb8aa3b, v38
	v_add_f32_e32 v36, v124, v120
	v_sub_f32_e32 v120, v123, v37
	v_exp_f32_e32 v123, v38
	v_sub_f32_e32 v38, v39, v37
	v_mul_f32_e32 v38, 0x3fb8aa3b, v38
	v_exp_f32_e32 v125, v38
	v_sub_f32_e32 v38, v40, v37
	v_mul_f32_e32 v38, 0x3fb8aa3b, v38
	v_exp_f32_e32 v126, v38
	v_sub_f32_e32 v38, v41, v37
	v_mul_f32_e32 v38, 0x3fb8aa3b, v38
	v_exp_f32_e32 v127, v38
	v_sub_f32_e32 v38, v42, v37
	v_mul_f32_e32 v38, 0x3fb8aa3b, v38
	v_exp_f32_e32 v42, v38
	v_sub_f32_e32 v38, v43, v37
	v_mul_f32_e32 v120, 0x3fb8aa3b, v120
	v_mul_f32_e32 v38, 0x3fb8aa3b, v38
	v_exp_f32_e32 v120, v120
	v_exp_f32_e32 v43, v38
	v_sub_f32_e32 v38, v44, v37
	v_mul_f32_e32 v38, 0x3fb8aa3b, v38
	v_exp_f32_e32 v44, v38
	v_sub_f32_e32 v38, v45, v37
	v_mul_f32_e32 v38, 0x3fb8aa3b, v38
	v_add_f32_e32 v36, v120, v36
	v_exp_f32_e32 v45, v38
	v_sub_f32_e32 v38, v46, v37
	v_add_f32_e32 v36, v123, v36
	v_mul_f32_e32 v38, 0x3fb8aa3b, v38
	v_add_f32_e32 v36, v125, v36
	v_exp_f32_e32 v46, v38
	v_sub_f32_e32 v38, v47, v37
	v_add_f32_e32 v36, v126, v36
	v_mul_f32_e32 v38, 0x3fb8aa3b, v38
	v_add_f32_e32 v36, v127, v36
	v_exp_f32_e32 v47, v38
	v_sub_f32_e32 v38, v48, v37
	v_add_f32_e32 v36, v42, v36
	v_mul_f32_e32 v38, 0x3fb8aa3b, v38
	v_add_f32_e32 v36, v43, v36
	v_exp_f32_e32 v48, v38
	v_sub_f32_e32 v38, v49, v37
	v_sub_f32_e32 v118, v118, v37
	v_add_f32_e32 v36, v44, v36
	v_mul_f32_e32 v38, 0x3fb8aa3b, v38
	v_mul_f32_e32 v118, 0x3fb8aa3b, v118
	v_add_f32_e32 v36, v45, v36
	v_exp_f32_e32 v49, v38
	v_add_f32_e32 v36, v46, v36
	v_exp_f32_e32 v38, v118
	v_add_f32_e32 v36, v47, v36
	v_add_f32_e32 v36, v48, v36
	v_add_f32_e32 v36, v49, v36
	v_fmac_f32_e32 v36, v119, v38
	v_pk_mul_f32 v[18:19], v[18:19], v[38:39] op_sel_hi:[1,0]
	v_pk_mul_f32 v[20:21], v[20:21], v[38:39] op_sel_hi:[1,0]
	v_pk_mul_f32 v[22:23], v[22:23], v[38:39] op_sel_hi:[1,0]
	v_pk_mul_f32 v[24:25], v[24:25], v[38:39] op_sel_hi:[1,0]
	v_pk_mul_f32 v[26:27], v[26:27], v[38:39] op_sel_hi:[1,0]
	v_pk_mul_f32 v[28:29], v[28:29], v[38:39] op_sel_hi:[1,0]
	v_pk_mul_f32 v[30:31], v[30:31], v[38:39] op_sel_hi:[1,0]
	v_pk_mul_f32 v[32:33], v[32:33], v[38:39] op_sel_hi:[1,0]
	v_pk_mul_f32 v[2:3], v[2:3], v[38:39] op_sel_hi:[1,0]
	v_pk_mul_f32 v[4:5], v[4:5], v[38:39] op_sel_hi:[1,0]
	v_pk_mul_f32 v[6:7], v[6:7], v[38:39] op_sel_hi:[1,0]
	v_pk_mul_f32 v[8:9], v[8:9], v[38:39] op_sel_hi:[1,0]
	v_pk_mul_f32 v[10:11], v[10:11], v[38:39] op_sel_hi:[1,0]
	v_pk_mul_f32 v[12:13], v[12:13], v[38:39] op_sel_hi:[1,0]
	v_pk_mul_f32 v[14:15], v[14:15], v[38:39] op_sel_hi:[1,0]
	v_pk_mul_f32 v[16:17], v[16:17], v[38:39] op_sel_hi:[1,0]
	v_cvt_pk_f16_f32 v38, v50, v51
	v_cvt_pk_f16_f32 v39, v52, v53
	v_cvt_pk_f16_f32 v40, v54, v55
	v_cvt_pk_f16_f32 v41, v56, v57
	v_mov_b32_e32 v118, v37
	s_waitcnt vmcnt(7)
	v_mfma_f32_32x32x16_f16 v[18:33], v[102:105], v[38:41], v[18:33]
	s_waitcnt vmcnt(5)
	v_mfma_f32_32x32x16_f16 v[2:17], v[110:113], v[38:41], v[2:17]
	v_cvt_pk_f16_f32 v38, v58, v59
	v_cvt_pk_f16_f32 v39, v60, v61
	v_cvt_pk_f16_f32 v40, v62, v63
	v_cvt_pk_f16_f32 v41, v64, v65
	s_nop 1
	v_mfma_f32_32x32x16_f16 v[18:33], v[90:93], v[38:41], v[18:33]
	s_waitcnt vmcnt(4)
	v_mfma_f32_32x32x16_f16 v[2:17], v[94:97], v[38:41], v[2:17]
	v_cvt_pk_f16_f32 v38, v121, v122
	v_cvt_pk_f16_f32 v39, v124, v120
	v_cvt_pk_f16_f32 v40, v123, v125
	v_cvt_pk_f16_f32 v41, v126, v127
	s_waitcnt vmcnt(3)
	s_nop 0
	v_mfma_f32_32x32x16_f16 v[18:33], v[98:101], v[38:41], v[18:33]
	s_waitcnt vmcnt(1)
	v_mfma_f32_32x32x16_f16 v[2:17], v[106:109], v[38:41], v[2:17]
	v_cvt_pk_f16_f32 v38, v42, v43
	v_cvt_pk_f16_f32 v39, v44, v45
	v_cvt_pk_f16_f32 v40, v46, v47
	v_cvt_pk_f16_f32 v41, v48, v49
	s_nop 1
	v_mfma_f32_32x32x16_f16 v[18:33], v[82:85], v[38:41], v[18:33]
	s_waitcnt vmcnt(0)
	v_mfma_f32_32x32x16_f16 v[2:17], v[86:89], v[38:41], v[2:17]
	s_cbranch_scc1 .LBB0_362

; #define MFMA32(a, b, c) __builtin_amdgcn_mfma_f32_32x32x16_f16((a), (b), (c), 0, 0, 0)
; DI int crow(int i, int h) { return (i & 3) + 8 * (i >> 2) + 4 * h; }
; template <int HD, int BIAS, bool FULL>
; DI void attn_block(const bf16_t* Kb, int ktb, const bf16_t* Vb, int vtb, int koff, int kpos0, int qp, float slope, const float* rel,
;                    const bf16x8 (&qf)[HD / 16], f32x16 (&o)[HD / 32], float& m, float& l) {
;     ...
;     bf16x8 kreg[NKT][KSQ];
; #pragma unroll
;     for (int kt = 0; kt < NKT; ++kt)
; #pragma unroll
;         for (int ks = 0; ks < KSQ; ++ks) kreg[kt][ks] = *(const bf16x8*)(Kb + (size_t)kt * ktb + ks * 512 + lane * 8);
;     constexpr int NS = FULL ? 4 : 1;
;     bf16x8 vreg[DT][NS];
;     auto loadV = [&]() {
; #pragma unroll
;         for (int si = 0; si < NS; ++si)
; #pragma unroll
;             for (int dt = 0; dt < DT; ++dt) { const int s = FULL ? si : s0; vreg[dt][si] = *(const bf16x8*)(Vb + (size_t)(s >> 1) * vtb + dt * 1024 + (s & 1) * 512 + lane * 8); }
;     };
;     if (VTOP) loadV();
;     __builtin_amdgcn_sched_barrier(0);
;     f32x16 st[NKT];
; #pragma unroll
;     for (int kt = 0; kt < NKT; ++kt) {
; #pragma unroll
;         for (int i = 0; i < 16; ++i) st[kt][i] = 0.f;
; #pragma unroll
;         for (int ks = 0; ks < KSQ; ++ks) st[kt] = MFMA32(kreg[kt][ks], qf[ks], st[kt]);
;     }
;     __builtin_amdgcn_sched_barrier(0);
;     if (!VTOP) loadV();
;     float mx = -1e30f;
; #pragma unroll
;     for (int kt = 0; kt < NKT; ++kt)
; #pragma unroll
;         for (int i = 0; i < 16; ++i) {
;             const int key = kt * 32 + crow(i, h);
;             float s = st[kt][i];
;             const int dk = dq + (kt * 32 + (i & 3) + 8 * (i >> 2));
;             if (BIAS == 1) s -= slope * (float)(dk < 0 ? -dk : dk);
;             if (BIAS == 2) { int d = dk < -256 ? -256 : (dk > 256 ? 256 : dk); s += rel[d + 256]; }
;             if (!FULL) { if (key < kbeg || key >= kend) s = -1e30f; }
.LBB0_497:
	v_mov_b32_e32 v0, v176
	s_add_u32 s68, s3, s4
	v_lshrrev_b32_e32 v35, 3, v0
	v_and_b32_e32 v0, 63, v0
	v_lshlrev_b32_e32 v0, 4, v0
	s_addc_u32 s69, s64, s5
	v_lshl_add_u64 v[48:49], s[68:69], 0, v[0:1]
	s_mov_b32 s68, 0x155b0000
	v_and_b32_e32 v35, 4, v35
	v_add_co_u32_e32 v50, vcc, s68, v48
	v_add_u32_e32 v119, v116, v35
	s_nop 0
	v_addc_co_u32_e32 v51, vcc, 0, v49, vcc
	s_mov_b32 s68, 0x155b8000
	global_load_dwordx4 v[36:39], v[50:51], off
	global_load_dwordx4 v[40:43], v[50:51], off offset:1024
	global_load_dwordx4 v[44:47], v[50:51], off offset:2048
	global_load_dwordx4 v[120:123], v[50:51], off offset:3072
	v_add_co_u32_e32 v50, vcc, s68, v48
	s_mov_b32 s68, 0x165d0000
	s_nop 0
	v_addc_co_u32_e32 v51, vcc, 0, v49, vcc
	global_load_dwordx4 v[124:127], v[50:51], off
	global_load_dwordx4 v[128:131], v[50:51], off offset:1024
	global_load_dwordx4 v[132:135], v[50:51], off offset:2048
	global_load_dwordx4 v[136:139], v[50:51], off offset:3072
	v_add_co_u32_e32 v50, vcc, s68, v48
	s_mov_b32 s68, 0x165d8000
	s_nop 0
	v_addc_co_u32_e32 v51, vcc, 0, v49, vcc
	v_add_co_u32_e32 v48, vcc, s68, v48
	global_load_dwordx4 v[102:105], v[50:51], off
	global_load_dwordx4 v[90:93], v[50:51], off offset:1024
	global_load_dwordx4 v[110:113], v[50:51], off offset:2048
	global_load_dwordx4 v[94:97], v[50:51], off offset:3072
	v_addc_co_u32_e32 v49, vcc, 0, v49, vcc
	global_load_dwordx4 v[98:101], v[48:49], off
	global_load_dwordx4 v[82:85], v[48:49], off offset:1024
	global_load_dwordx4 v[106:109], v[48:49], off offset:2048
	global_load_dwordx4 v[86:89], v[48:49], off offset:3072
	v_mov_b32_e32 v118, v34
	s_waitcnt vmcnt(15)
	v_mfma_f32_32x32x16_f16 v[50:65], v[36:39], v[66:69], 0
	s_waitcnt vmcnt(14)
	v_mfma_f32_32x32x16_f16 v[50:65], v[40:43], v[70:73], v[50:65]
	s_waitcnt vmcnt(13)
	v_mfma_f32_32x32x16_f16 v[50:65], v[44:47], v[74:77], v[50:65]
	s_waitcnt vmcnt(11)
	v_mfma_f32_32x32x16_f16 v[34:49], v[124:127], v[66:69], 0
	s_waitcnt vmcnt(10)
	v_mfma_f32_32x32x16_f16 v[34:49], v[128:131], v[70:73], v[34:49]
	s_waitcnt vmcnt(9)
	v_mfma_f32_32x32x16_f16 v[34:49], v[132:135], v[74:77], v[34:49]
	s_waitcnt vmcnt(8)
	v_mfma_f32_32x32x16_f16 v[34:49], v[136:139], v[78:81], v[34:49]
	v_mfma_f32_32x32x16_f16 v[50:65], v[120:123], v[78:81], v[50:65]
	v_cmp_lt_i32_e32 vcc, 0xfffffec5, v119
	s_cbranch_vccnz .Lbf_p2_slow
	v_mov_b32_e32 v142, s67
	ds_read_b32 v143, v142
	ds_read_b32 v144, v142
	ds_read_b32 v145, v142
	ds_read_b32 v146, v142
	ds_read_b32 v147, v142
	ds_read_b32 v148, v142
	ds_read_b32 v149, v142
	ds_read_b32 v150, v142
	ds_read_b32 v151, v142
	ds_read_b32 v152, v142
	ds_read_b32 v153, v142
	ds_read_b32 v154, v142
	ds_read_b32 v155, v142
	ds_read_b32 v156, v142
	ds_read_b32 v157, v142
	ds_read_b32 v158, v142
	ds_read_b32 v159, v142
	ds_read_b32 v160, v142
	ds_read_b32 v161, v142
	ds_read_b32 v162, v142
	ds_read_b32 v163, v142
	ds_read_b32 v164, v142
	ds_read_b32 v165, v142
	ds_read_b32 v166, v142
	ds_read_b32 v167, v142
	ds_read_b32 v168, v142
	ds_read_b32 v169, v142
	ds_read_b32 v170, v142
	ds_read_b32 v171, v142
	ds_read_b32 v172, v142
	ds_read_b32 v173, v142
	ds_read_b32 v142, v142
	s_branch .Lbf_p2_join
.Lbf_p2_slow:
	v_add_u32_e32 v142, 2, v119
	v_med3_i32 v142, v142, s45, v186
	v_lshl_add_u32 v142, v142, 2, s67
	ds_read_b32 v142, v142 offset:1024
	v_med3_i32 v143, v119, s45, v186
	v_lshl_add_u32 v143, v143, 2, s67
	ds_read_b32 v143, v143 offset:1024
	v_add_u32_e32 v144, 3, v119
	v_med3_i32 v144, v144, s45, v186
	v_lshl_add_u32 v144, v144, 2, s67
	ds_read_b32 v144, v144 offset:1024
	v_add_u32_e32 v145, 8, v119
	v_med3_i32 v145, v145, s45, v186
	v_lshl_add_u32 v145, v145, 2, s67
	ds_read_b32 v145, v145 offset:1024
	v_add_u32_e32 v146, 9, v119
	v_med3_i32 v146, v146, s45, v186
	v_lshl_add_u32 v146, v146, 2, s67
	ds_read_b32 v146, v146 offset:1024
	v_add_u32_e32 v147, 10, v119
	v_med3_i32 v147, v147, s45, v186
	v_lshl_add_u32 v147, v147, 2, s67
	ds_read_b32 v147, v147 offset:1024
	v_add_u32_e32 v148, 11, v119
	v_med3_i32 v148, v148, s45, v186
	v_lshl_add_u32 v148, v148, 2, s67
	ds_read_b32 v148, v148 offset:1024
	v_add_u32_e32 v149, 16, v119
	v_med3_i32 v149, v149, s45, v186
	v_lshl_add_u32 v149, v149, 2, s67
	ds_read_b32 v149, v149 offset:1024
	v_add_u32_e32 v150, 17, v119
	v_med3_i32 v150, v150, s45, v186
	v_lshl_add_u32 v150, v150, 2, s67
	ds_read_b32 v150, v150 offset:1024
	v_add_u32_e32 v151, 18, v119
	v_med3_i32 v151, v151, s45, v186
	v_lshl_add_u32 v151, v151, 2, s67
	ds_read_b32 v151, v151 offset:1024
	v_add_u32_e32 v152, 19, v119
	v_med3_i32 v152, v152, s45, v186
	v_lshl_add_u32 v152, v152, 2, s67
	ds_read_b32 v152, v152 offset:1024
	v_add_u32_e32 v153, 24, v119
	v_med3_i32 v153, v153, s45, v186
	v_lshl_add_u32 v153, v153, 2, s67
	ds_read_b32 v153, v153 offset:1024
	v_add_u32_e32 v154, 25, v119
	v_med3_i32 v154, v154, s45, v186
	v_lshl_add_u32 v154, v154, 2, s67
	ds_read_b32 v154, v154 offset:1024
	v_add_u32_e32 v155, 26, v119
	v_med3_i32 v155, v155, s45, v186
	v_lshl_add_u32 v155, v155, 2, s67
	ds_read_b32 v155, v155 offset:1024
	v_add_u32_e32 v156, 27, v119
	v_med3_i32 v156, v156, s45, v186
	v_lshl_add_u32 v156, v156, 2, s67
	ds_read_b32 v156, v156 offset:1024
	v_add_u32_e32 v157, 32, v119
	v_med3_i32 v157, v157, s45, v186
	v_lshl_add_u32 v157, v157, 2, s67
	ds_read_b32 v157, v157 offset:1024
	v_add_u32_e32 v158, 33, v119
	v_med3_i32 v158, v158, s45, v186
	v_lshl_add_u32 v158, v158, 2, s67
	ds_read_b32 v158, v158 offset:1024
	v_add_u32_e32 v159, 34, v119
	v_med3_i32 v159, v159, s45, v186
	v_lshl_add_u32 v159, v159, 2, s67
	ds_read_b32 v159, v159 offset:1024
	v_add_u32_e32 v160, 1, v119
	v_med3_i32 v160, v160, s45, v186
; DI int crow(int i, int h) { return (i & 3) + 8 * (i >> 2) + 4 * h; }
; template <int HD, int BIAS, bool FULL>
; DI void attn_block(const bf16_t* Kb, int ktb, const bf16_t* Vb, int vtb, int koff, int kpos0, int qp, float slope, const float* rel,
;                    const bf16x8 (&qf)[HD / 16], f32x16 (&o)[HD / 32], float& m, float& l) {
;     ...
;     for (int kt = 0; kt < NKT; ++kt)
; #pragma unroll
;         for (int i = 0; i < 16; ++i) {
;             const int key = kt * 32 + crow(i, h);
;             float s = st[kt][i];
;             const int dk = dq + (kt * 32 + (i & 3) + 8 * (i >> 2));
;             if (BIAS == 1) s -= slope * (float)(dk < 0 ? -dk : dk);
;             if (BIAS == 2) { int d = dk < -256 ? -256 : (dk > 256 ? 256 : dk); s += rel[d + 256]; }
;             if (!FULL) { if (key < kbeg || key >= kend) s = -1e30f; }
;             st[kt][i] = s; mx = fmaxf(mx, s);
;         }
;     mx = fmaxf(mx, __shfl_xor(mx, 32));
	v_lshl_add_u32 v160, v160, 2, s67
	v_add_u32_e32 v161, 35, v119
	v_med3_i32 v161, v161, s45, v186
	v_lshl_add_u32 v161, v161, 2, s67
	ds_read_b32 v160, v160 offset:1024
	ds_read_b32 v161, v161 offset:1024
	v_add_u32_e32 v162, 40, v119
	v_med3_i32 v162, v162, s45, v186
	v_lshl_add_u32 v162, v162, 2, s67
	ds_read_b32 v162, v162 offset:1024
	v_add_u32_e32 v163, 41, v119
	v_med3_i32 v163, v163, s45, v186
	v_lshl_add_u32 v163, v163, 2, s67
	ds_read_b32 v163, v163 offset:1024
	v_add_u32_e32 v164, 42, v119
	v_med3_i32 v164, v164, s45, v186
	v_lshl_add_u32 v164, v164, 2, s67
	ds_read_b32 v164, v164 offset:1024
	v_add_u32_e32 v165, 43, v119
	v_med3_i32 v165, v165, s45, v186
	v_lshl_add_u32 v165, v165, 2, s67
	ds_read_b32 v165, v165 offset:1024
	v_add_u32_e32 v166, 48, v119
	v_med3_i32 v166, v166, s45, v186
	v_lshl_add_u32 v166, v166, 2, s67
	ds_read_b32 v166, v166 offset:1024
	v_add_u32_e32 v167, 49, v119
	v_med3_i32 v167, v167, s45, v186
	v_lshl_add_u32 v167, v167, 2, s67
	ds_read_b32 v167, v167 offset:1024
	v_add_u32_e32 v168, 50, v119
	v_med3_i32 v168, v168, s45, v186
	v_lshl_add_u32 v168, v168, 2, s67
	ds_read_b32 v168, v168 offset:1024
	v_add_u32_e32 v169, 51, v119
	v_med3_i32 v169, v169, s45, v186
	v_lshl_add_u32 v169, v169, 2, s67
	ds_read_b32 v169, v169 offset:1024
	v_add_u32_e32 v170, 56, v119
	v_med3_i32 v170, v170, s45, v186
	v_lshl_add_u32 v170, v170, 2, s67
	ds_read_b32 v170, v170 offset:1024
	v_add_u32_e32 v171, 57, v119
	v_med3_i32 v171, v171, s45, v186
	v_lshl_add_u32 v171, v171, 2, s67
	ds_read_b32 v171, v171 offset:1024
	v_add_u32_e32 v172, 58, v119
	v_med3_i32 v172, v172, s45, v186
	v_lshl_add_u32 v172, v172, 2, s67
	ds_read_b32 v172, v172 offset:1024
	v_add_u32_e32 v173, 59, v119
	v_med3_i32 v173, v173, s45, v186
	v_lshl_add_u32 v173, v173, 2, s67
	ds_read_b32 v173, v173 offset:1024
.Lbf_p2_join:
	s_waitcnt lgkmcnt(0)
	v_cmp_lt_i32_e32 vcc, v188, v189
	s_nop 2
	v_add_f32_e32 v52, v52, v142
	s_add_u32 s4, s4, 0x10000
	s_addc_u32 s5, s5, 0
	v_add_u32_e32 v116, 64, v116
	s_cmp_lg_u32 s1, s4
	v_add_f32_e32 v53, v53, v144
	v_add_f32_e32 v54, v54, v145
	v_add_f32_e32 v55, v55, v146
	v_add_f32_e32 v56, v56, v147
	v_add_f32_e32 v57, v57, v148
	v_add_f32_e32 v58, v58, v149
	v_add_f32_e32 v59, v59, v150
	v_add_f32_e32 v60, v60, v151
	v_add_f32_e32 v61, v61, v152
	v_add_f32_e32 v62, v62, v153
	v_add_f32_e32 v63, v63, v154
	v_add_f32_e32 v64, v64, v155
	v_add_f32_e32 v65, v65, v156
	v_add_f32_e32 v34, v34, v157
	v_add_f32_e32 v120, v35, v158
	v_add_f32_e32 v50, v50, v143
	v_add_f32_e32 v36, v36, v159
	v_add_f32_e32 v51, v51, v160
	v_add_f32_e32 v37, v37, v161
	v_max3_f32 v0, v50, s46, v51
	v_max3_f32 v0, v0, v52, v53
	v_max3_f32 v0, v0, v54, v55
	v_max3_f32 v0, v0, v56, v57
	v_add_f32_e32 v38, v38, v162
	v_max3_f32 v0, v0, v58, v59
	v_max3_f32 v0, v0, v60, v61
	v_max3_f32 v0, v0, v62, v63
	v_max3_f32 v0, v0, v64, v65
	v_add_f32_e32 v39, v39, v163
	v_max3_f32 v0, v0, v34, v120
	v_max3_f32 v0, v0, v36, v37
	v_max3_f32 v0, v0, v38, v39
	v_add_f32_e32 v40, v40, v164
	v_add_f32_e32 v41, v41, v165
	v_max3_f32 v0, v0, v40, v41
	v_add_f32_e32 v42, v42, v166
	v_add_f32_e32 v43, v43, v167
	v_max3_f32 v0, v0, v42, v43
	v_add_f32_e32 v44, v44, v168
	v_add_f32_e32 v45, v45, v169
	v_max3_f32 v0, v0, v44, v45
	v_add_f32_e32 v46, v46, v170
	v_add_f32_e32 v47, v47, v171
	v_max3_f32 v0, v0, v46, v47
	v_add_f32_e32 v48, v48, v172
	v_add_f32_e32 v49, v49, v173
	v_max3_f32 v35, v0, v48, v49
	v_cndmask_b32_e32 v0, v187, v188, vcc
	v_lshlrev_b32_e32 v0, 2, v0
	ds_bpermute_b32 v119, v0, v35
	s_waitcnt lgkmcnt(0)
; #define MFMA32(a, b, c) __builtin_amdgcn_mfma_f32_32x32x16_f16((a), (b), (c), 0, 0, 0)
; DI unsigned pk2(float lo, float hi) { f32x2 v = {lo, hi}; bf2_t b = __builtin_convertvector(v, bf2_t); return __builtin_bit_cast(unsigned, b); }
; template <int HD, int BIAS, bool FULL>
; DI void attn_block(const bf16_t* Kb, int ktb, const bf16_t* Vb, int vtb, int koff, int kpos0, int qp, float slope, const float* rel,
;                    const bf16x8 (&qf)[HD / 16], f32x16 (&o)[HD / 32], float& m, float& l) {
;     ...
;     const float mn = fmaxf(m, mx);
;     const float alpha = __builtin_amdgcn_exp2f((m - mn) * LOG2E);
;     m = mn;
;     float ps = 0.f;
; #pragma unroll
;     for (int kt = 0; kt < NKT; ++kt)
; #pragma unroll
;         for (int i = 0; i < 16; ++i) { const float pv = __builtin_amdgcn_exp2f((st[kt][i] - mn) * LOG2E); st[kt][i] = pv; ps += pv; }
;     l = l * alpha + ps;
; #pragma unroll
;     for (int dt = 0; dt < DT; ++dt)
; #pragma unroll
;         for (int i = 0; i < 16; ++i) o[dt][i] *= alpha;
; #pragma unroll
;     for (int si = 0; si < NS; ++si) {
;         u32x4 pw;
;         if (FULL) { const int kt = si >> 1, b0 = (si & 1) * 8; pw = (u32x4){pk2(st[kt][b0], st[kt][b0 + 1]), pk2(st[kt][b0 + 2], st[kt][b0 + 3]), pk2(st[kt][b0 + 4], st[kt][b0 + 5]), pk2(st[kt][b0 + 6], st[kt][b0 + 7])}; }
;         else {
;             const u32x4 lo = {pk2(st[0][0], st[0][1]), pk2(st[0][2], st[0][3]), pk2(st[0][4], st[0][5]), pk2(st[0][6], st[0][7])};
;             const u32x4 hi = {pk2(st[0][8], st[0][9]), pk2(st[0][10], st[0][11]), pk2(st[0][12], st[0][13]), pk2(st[0][14], st[0][15])};
;             pw = (s0 & 1) ? hi : lo;
;         }
;         const bf16x8 pf = __builtin_bit_cast(bf16x8, pw);
; #pragma unroll
;         for (int dt = 0; dt < DT; ++dt) o[dt] = MFMA32(vreg[dt][si], pf, o[dt]);
;     }
; }
; template <int HD, int BIAS> ...
;     ...
;     const float lt = l + __shfl_xor(l, 32);
;     const float inv = 1.f / lt;
	v_max3_f32 v35, v117, v35, v119
	v_sub_f32_e32 v50, v50, v35
	v_mul_f32_e32 v50, 0x3fb8aa3b, v50
	v_sub_f32_e32 v51, v51, v35
	v_exp_f32_e32 v50, v50
	v_mul_f32_e32 v51, 0x3fb8aa3b, v51
	v_sub_f32_e32 v52, v52, v35
	v_exp_f32_e32 v51, v51
	v_mul_f32_e32 v52, 0x3fb8aa3b, v52
	v_sub_f32_e32 v53, v53, v35
	v_exp_f32_e32 v52, v52
	v_mul_f32_e32 v53, 0x3fb8aa3b, v53
	v_sub_f32_e32 v54, v54, v35
	v_exp_f32_e32 v53, v53
	v_mul_f32_e32 v54, 0x3fb8aa3b, v54
	v_sub_f32_e32 v55, v55, v35
	v_add_f32_e32 v119, 0, v50
	v_exp_f32_e32 v54, v54
	v_mul_f32_e32 v55, 0x3fb8aa3b, v55
	v_sub_f32_e32 v56, v56, v35
	v_add_f32_e32 v119, v51, v119
	v_exp_f32_e32 v55, v55
	v_mul_f32_e32 v56, 0x3fb8aa3b, v56
	v_sub_f32_e32 v57, v57, v35
	v_add_f32_e32 v119, v52, v119
	v_exp_f32_e32 v56, v56
	v_mul_f32_e32 v57, 0x3fb8aa3b, v57
	v_sub_f32_e32 v58, v58, v35
	v_add_f32_e32 v119, v53, v119
	v_exp_f32_e32 v57, v57
	v_mul_f32_e32 v58, 0x3fb8aa3b, v58
	v_sub_f32_e32 v59, v59, v35
	v_add_f32_e32 v119, v54, v119
	v_exp_f32_e32 v58, v58
	v_mul_f32_e32 v59, 0x3fb8aa3b, v59
	v_sub_f32_e32 v60, v60, v35
	v_add_f32_e32 v119, v55, v119
	v_exp_f32_e32 v59, v59
	v_mul_f32_e32 v60, 0x3fb8aa3b, v60
	v_sub_f32_e32 v61, v61, v35
	v_add_f32_e32 v119, v56, v119
	v_exp_f32_e32 v60, v60
	v_mul_f32_e32 v61, 0x3fb8aa3b, v61
	v_sub_f32_e32 v62, v62, v35
	v_add_f32_e32 v119, v57, v119
	v_exp_f32_e32 v61, v61
	v_mul_f32_e32 v62, 0x3fb8aa3b, v62
	v_sub_f32_e32 v63, v63, v35
	v_add_f32_e32 v119, v58, v119
	v_exp_f32_e32 v62, v62
	v_mul_f32_e32 v63, 0x3fb8aa3b, v63
	v_sub_f32_e32 v64, v64, v35
	v_add_f32_e32 v119, v59, v119
	v_exp_f32_e32 v63, v63
	v_mul_f32_e32 v64, 0x3fb8aa3b, v64
	v_sub_f32_e32 v65, v65, v35
	v_add_f32_e32 v119, v60, v119
	v_exp_f32_e32 v64, v64
	v_mul_f32_e32 v65, 0x3fb8aa3b, v65
	v_sub_f32_e32 v34, v34, v35
	v_add_f32_e32 v119, v61, v119
	v_exp_f32_e32 v65, v65
	v_mul_f32_e32 v34, 0x3fb8aa3b, v34
	v_add_f32_e32 v119, v62, v119
	v_exp_f32_e32 v121, v34
	v_add_f32_e32 v119, v63, v119
	v_add_f32_e32 v119, v64, v119
	v_sub_f32_e32 v36, v36, v35
	v_add_f32_e32 v119, v65, v119
	v_mul_f32_e32 v36, 0x3fb8aa3b, v36
	v_add_f32_e32 v34, v121, v119
	v_sub_f32_e32 v119, v120, v35
	v_exp_f32_e32 v120, v36
	v_sub_f32_e32 v36, v37, v35
	v_mul_f32_e32 v36, 0x3fb8aa3b, v36
	v_exp_f32_e32 v122, v36
	v_sub_f32_e32 v36, v38, v35
	v_mul_f32_e32 v36, 0x3fb8aa3b, v36
	v_exp_f32_e32 v123, v36
	v_sub_f32_e32 v36, v39, v35
	v_mul_f32_e32 v36, 0x3fb8aa3b, v36
	v_exp_f32_e32 v124, v36
	v_sub_f32_e32 v36, v40, v35
	v_mul_f32_e32 v36, 0x3fb8aa3b, v36
	v_exp_f32_e32 v40, v36
	v_sub_f32_e32 v36, v41, v35
	v_mul_f32_e32 v36, 0x3fb8aa3b, v36
	v_exp_f32_e32 v41, v36
	v_sub_f32_e32 v36, v42, v35
	v_mul_f32_e32 v119, 0x3fb8aa3b, v119
	v_mul_f32_e32 v36, 0x3fb8aa3b, v36
	v_exp_f32_e32 v119, v119
	v_exp_f32_e32 v42, v36
	v_sub_f32_e32 v36, v43, v35
	v_mul_f32_e32 v36, 0x3fb8aa3b, v36
	v_exp_f32_e32 v43, v36
	v_sub_f32_e32 v36, v44, v35
	v_mul_f32_e32 v36, 0x3fb8aa3b, v36
	v_add_f32_e32 v34, v119, v34
	v_exp_f32_e32 v44, v36
	v_sub_f32_e32 v36, v45, v35
	v_add_f32_e32 v34, v120, v34
	v_mul_f32_e32 v36, 0x3fb8aa3b, v36
	v_add_f32_e32 v34, v122, v34
	v_exp_f32_e32 v45, v36
	v_sub_f32_e32 v36, v46, v35
	v_add_f32_e32 v34, v123, v34
	v_mul_f32_e32 v36, 0x3fb8aa3b, v36
	v_add_f32_e32 v34, v124, v34
	v_exp_f32_e32 v46, v36
	v_sub_f32_e32 v36, v47, v35
	v_add_f32_e32 v34, v40, v34
	v_mul_f32_e32 v36, 0x3fb8aa3b, v36
	v_add_f32_e32 v34, v41, v34
	v_exp_f32_e32 v47, v36
	v_sub_f32_e32 v36, v48, v35
	v_add_f32_e32 v34, v42, v34
	v_mul_f32_e32 v36, 0x3fb8aa3b, v36
	v_add_f32_e32 v34, v43, v34
	v_exp_f32_e32 v48, v36
	v_sub_f32_e32 v36, v49, v35
	v_sub_f32_e32 v117, v117, v35
	v_add_f32_e32 v34, v44, v34
	v_mul_f32_e32 v36, 0x3fb8aa3b, v36
	v_mul_f32_e32 v117, 0x3fb8aa3b, v117
	v_add_f32_e32 v34, v45, v34
	v_exp_f32_e32 v49, v36
	v_add_f32_e32 v34, v46, v34
	v_exp_f32_e32 v36, v117
	v_add_f32_e32 v34, v47, v34
	v_add_f32_e32 v34, v48, v34
	v_add_f32_e32 v34, v49, v34
	v_fmac_f32_e32 v34, v118, v36
	v_pk_mul_f32 v[18:19], v[18:19], v[36:37] op_sel_hi:[1,0]
	v_pk_mul_f32 v[20:21], v[20:21], v[36:37] op_sel_hi:[1,0]
	v_pk_mul_f32 v[22:23], v[22:23], v[36:37] op_sel_hi:[1,0]
	v_pk_mul_f32 v[24:25], v[24:25], v[36:37] op_sel_hi:[1,0]
	v_pk_mul_f32 v[26:27], v[26:27], v[36:37] op_sel_hi:[1,0]
	v_pk_mul_f32 v[28:29], v[28:29], v[36:37] op_sel_hi:[1,0]
	v_pk_mul_f32 v[30:31], v[30:31], v[36:37] op_sel_hi:[1,0]
	v_pk_mul_f32 v[32:33], v[32:33], v[36:37] op_sel_hi:[1,0]
	v_pk_mul_f32 v[2:3], v[2:3], v[36:37] op_sel_hi:[1,0]
	v_pk_mul_f32 v[4:5], v[4:5], v[36:37] op_sel_hi:[1,0]
	v_pk_mul_f32 v[6:7], v[6:7], v[36:37] op_sel_hi:[1,0]
	v_pk_mul_f32 v[8:9], v[8:9], v[36:37] op_sel_hi:[1,0]
	v_pk_mul_f32 v[10:11], v[10:11], v[36:37] op_sel_hi:[1,0]
	v_pk_mul_f32 v[12:13], v[12:13], v[36:37] op_sel_hi:[1,0]
	v_pk_mul_f32 v[14:15], v[14:15], v[36:37] op_sel_hi:[1,0]
	v_pk_mul_f32 v[16:17], v[16:17], v[36:37] op_sel_hi:[1,0]
	v_cvt_pk_f16_f32 v36, v50, v51
	v_cvt_pk_f16_f32 v37, v52, v53
	v_cvt_pk_f16_f32 v38, v54, v55
	v_cvt_pk_f16_f32 v39, v56, v57
	v_mov_b32_e32 v117, v35
	s_waitcnt vmcnt(7)
	v_mfma_f32_32x32x16_f16 v[18:33], v[102:105], v[36:39], v[18:33]
	s_waitcnt vmcnt(5)
	v_mfma_f32_32x32x16_f16 v[2:17], v[110:113], v[36:39], v[2:17]
	v_cvt_pk_f16_f32 v36, v58, v59
	v_cvt_pk_f16_f32 v37, v60, v61
	v_cvt_pk_f16_f32 v38, v62, v63
	v_cvt_pk_f16_f32 v39, v64, v65
	s_nop 1
	v_mfma_f32_32x32x16_f16 v[18:33], v[90:93], v[36:39], v[18:33]
	s_waitcnt vmcnt(4)
	v_mfma_f32_32x32x16_f16 v[2:17], v[94:97], v[36:39], v[2:17]
	v_cvt_pk_f16_f32 v36, v121, v119
	v_cvt_pk_f16_f32 v37, v120, v122
	v_cvt_pk_f16_f32 v38, v123, v124
	v_cvt_pk_f16_f32 v39, v40, v41
	s_waitcnt vmcnt(3)
	s_nop 0
	v_mfma_f32_32x32x16_f16 v[18:33], v[98:101], v[36:39], v[18:33]
	s_waitcnt vmcnt(1)
	v_mfma_f32_32x32x16_f16 v[2:17], v[106:109], v[36:39], v[2:17]
	v_cvt_pk_f16_f32 v36, v42, v43
	v_cvt_pk_f16_f32 v37, v44, v45
	v_cvt_pk_f16_f32 v38, v46, v47
	v_cvt_pk_f16_f32 v39, v48, v49
	s_nop 1
	v_mfma_f32_32x32x16_f16 v[18:33], v[82:85], v[36:39], v[18:33]
	s_waitcnt vmcnt(0)
	v_mfma_f32_32x32x16_f16 v[2:17], v[86:89], v[36:39], v[2:17]
	s_cbranch_scc1 .LBB0_497
	ds_bpermute_b32 v35, v0, v34
	s_lshl_b32 s2, s2, 1
	s_add_u32 s2, s8, s2
	v_lshlrev_b32_e32 v0, 1, v114
	s_addc_u32 s3, s9, 0
	s_waitcnt lgkmcnt(0)
	v_add_f32_e32 v36, v34, v35
	v_lshl_add_u64 v[34:35], s[2:3], 0, v[0:1]
	s_mov_b64 s[2:3], 0
	s_movk_i32 s17, 0x810
	s_movk_i32 s64, 0x3fff
